# stack3 + gate projection K loop with a 4-deep x-fragment register ring (three trips of loads in flight)
# speedup vs baseline: 1.0179x; 1.0179x over previous
; #define LAS __attribute__((address_space(3)))
; DI void phase_gates(const Params& P, int l, int bid, int nb, LAS unsigned char* lds) {
;     ...
;     for (int t = bid * 8 + wid; t < MTOK / 32; t += nb * 8) {
;         const bf16_t* ap = XB + (size_t)(t * 32 + r) * DM + 32 * h;
;         f32x16 acc; for (int i = 0; i < 16; ++i) acc[i] = 0.f;
;         bf16x8 a[8], an[8];
; #pragma unroll
;         for (int j = 0; j < 8; ++j) a[j] = *(const bf16x8*)(ap + (j >> 2) * 64 + 8 * (j & 3));
; #pragma unroll 1
;         for (int kb = 0; kb < DM; kb += 128) {
;             if (kb + 128 < DM) {
; #pragma unroll
;                 for (int j = 0; j < 8; ++j) an[j] = *(const bf16x8*)(ap + kb + 128 + (j >> 2) * 64 + 8 * (j & 3)); }
; #pragma unroll
;             for (int j = 0; j < 8; ++j) { const bf16x8 bj = *(const LAS bf16x8*)(bp + (kb + (j >> 2) * 64 + 8 * (j & 3)) * 2);
;                 acc = __builtin_amdgcn_mfma_f32_32x32x16_bf16(a[j], bj, acc, 0, 0, 0); }
.LBB0_190:
	v_lshlrev_b32_e32 v82, 5, v95
	v_or_b32_e32 v2, v82, v1
	v_ashrrev_i32_e32 v3, 31, v2
	v_lshlrev_b64 v[2:3], 12, v[2:3]
	v_lshl_add_u64 v[240:241], v[84:85], 0, v[2:3]
	global_load_dwordx4 v[18:21], v[240:241], off
	global_load_dwordx4 v[22:25], v[240:241], off offset:16
	global_load_dwordx4 v[26:29], v[240:241], off offset:32
	global_load_dwordx4 v[30:33], v[240:241], off offset:48
	global_load_dwordx4 v[34:37], v[240:241], off offset:128
	global_load_dwordx4 v[38:41], v[240:241], off offset:144
	global_load_dwordx4 v[42:45], v[240:241], off offset:160
	global_load_dwordx4 v[46:49], v[240:241], off offset:176
	global_load_dwordx4 v[50:53], v[240:241], off offset:256
	global_load_dwordx4 v[54:57], v[240:241], off offset:272
	global_load_dwordx4 v[58:61], v[240:241], off offset:288
	global_load_dwordx4 v[62:65], v[240:241], off offset:304
	global_load_dwordx4 v[66:69], v[240:241], off offset:384
	global_load_dwordx4 v[70:73], v[240:241], off offset:400
	global_load_dwordx4 v[74:77], v[240:241], off offset:416
	global_load_dwordx4 v[78:81], v[240:241], off offset:432
	global_load_dwordx4 v[164:167], v[240:241], off offset:512
	global_load_dwordx4 v[168:171], v[240:241], off offset:528
	global_load_dwordx4 v[172:175], v[240:241], off offset:544
	global_load_dwordx4 v[176:179], v[240:241], off offset:560
	global_load_dwordx4 v[180:183], v[240:241], off offset:640
	global_load_dwordx4 v[184:187], v[240:241], off offset:656
	global_load_dwordx4 v[188:191], v[240:241], off offset:672
	global_load_dwordx4 v[192:195], v[240:241], off offset:688
	v_mov_b32_e32 v2, 0
	v_mov_b32_e32 v3, v83
	v_mov_b32_e32 v4, v83
	v_mov_b32_e32 v5, v83
	v_mov_b32_e32 v6, v83
	v_mov_b32_e32 v7, v83
	v_mov_b32_e32 v8, v83
	v_mov_b32_e32 v9, v83
	v_mov_b32_e32 v10, v83
	v_mov_b32_e32 v11, v83
	v_mov_b32_e32 v12, v83
	v_mov_b32_e32 v13, v83
	v_mov_b32_e32 v14, v83
	v_mov_b32_e32 v15, v83
	v_mov_b32_e32 v16, v83
	v_mov_b32_e32 v17, v83
	global_load_dwordx4 v[208:211], v[240:241], off offset:768
	global_load_dwordx4 v[212:215], v[240:241], off offset:784
	global_load_dwordx4 v[216:219], v[240:241], off offset:800
	global_load_dwordx4 v[220:223], v[240:241], off offset:816
	global_load_dwordx4 v[224:227], v[240:241], off offset:896
	global_load_dwordx4 v[228:231], v[240:241], off offset:912
	global_load_dwordx4 v[232:235], v[240:241], off offset:928
	global_load_dwordx4 v[236:239], v[240:241], off offset:944
	ds_read_b128 v[108:111], v96
	ds_read_b128 v[112:115], v96 offset:16
	ds_read_b128 v[116:119], v96 offset:32
	ds_read_b128 v[120:123], v96 offset:48
	ds_read_b128 v[124:127], v96 offset:128
	ds_read_b128 v[148:151], v96 offset:144
	ds_read_b128 v[152:155], v96 offset:160
	ds_read_b128 v[156:159], v96 offset:176
	s_waitcnt vmcnt(31) lgkmcnt(7)
	v_mfma_f32_32x32x16_bf16 v[2:17], v[18:21], v[108:111], v[2:17]
	s_waitcnt vmcnt(30) lgkmcnt(6)
	v_mfma_f32_32x32x16_bf16 v[2:17], v[22:25], v[112:115], v[2:17]
	s_waitcnt vmcnt(29) lgkmcnt(5)
	v_mfma_f32_32x32x16_bf16 v[2:17], v[26:29], v[116:119], v[2:17]
	s_waitcnt vmcnt(28) lgkmcnt(4)
	v_mfma_f32_32x32x16_bf16 v[2:17], v[30:33], v[120:123], v[2:17]
	s_waitcnt vmcnt(27) lgkmcnt(3)
	v_mfma_f32_32x32x16_bf16 v[2:17], v[34:37], v[124:127], v[2:17]
	s_waitcnt vmcnt(26) lgkmcnt(2)
	v_mfma_f32_32x32x16_bf16 v[2:17], v[38:41], v[148:151], v[2:17]
	s_waitcnt vmcnt(25) lgkmcnt(1)
	v_mfma_f32_32x32x16_bf16 v[2:17], v[42:45], v[152:155], v[2:17]
	s_waitcnt vmcnt(24) lgkmcnt(0)
	v_mfma_f32_32x32x16_bf16 v[2:17], v[46:49], v[156:159], v[2:17]
	global_load_dwordx4 v[18:21], v[240:241], off offset:1024
	global_load_dwordx4 v[22:25], v[240:241], off offset:1040
	global_load_dwordx4 v[26:29], v[240:241], off offset:1056
	global_load_dwordx4 v[30:33], v[240:241], off offset:1072
	global_load_dwordx4 v[34:37], v[240:241], off offset:1152
	global_load_dwordx4 v[38:41], v[240:241], off offset:1168
	global_load_dwordx4 v[42:45], v[240:241], off offset:1184
	global_load_dwordx4 v[46:49], v[240:241], off offset:1200
	ds_read_b128 v[108:111], v96 offset:256
	ds_read_b128 v[112:115], v96 offset:272
	ds_read_b128 v[116:119], v96 offset:288
	ds_read_b128 v[120:123], v96 offset:304
	ds_read_b128 v[124:127], v96 offset:384
	ds_read_b128 v[148:151], v96 offset:400
	ds_read_b128 v[152:155], v96 offset:416
	ds_read_b128 v[156:159], v96 offset:432
	s_waitcnt vmcnt(31) lgkmcnt(7)
	v_mfma_f32_32x32x16_bf16 v[2:17], v[50:53], v[108:111], v[2:17]
	s_waitcnt vmcnt(30) lgkmcnt(6)
	v_mfma_f32_32x32x16_bf16 v[2:17], v[54:57], v[112:115], v[2:17]
	s_waitcnt vmcnt(29) lgkmcnt(5)
	v_mfma_f32_32x32x16_bf16 v[2:17], v[58:61], v[116:119], v[2:17]
	s_waitcnt vmcnt(28) lgkmcnt(4)
	v_mfma_f32_32x32x16_bf16 v[2:17], v[62:65], v[120:123], v[2:17]
	s_waitcnt vmcnt(27) lgkmcnt(3)
	v_mfma_f32_32x32x16_bf16 v[2:17], v[66:69], v[124:127], v[2:17]
	s_waitcnt vmcnt(26) lgkmcnt(2)
	v_mfma_f32_32x32x16_bf16 v[2:17], v[70:73], v[148:151], v[2:17]
	s_waitcnt vmcnt(25) lgkmcnt(1)
	v_mfma_f32_32x32x16_bf16 v[2:17], v[74:77], v[152:155], v[2:17]
	s_waitcnt vmcnt(24) lgkmcnt(0)
	v_mfma_f32_32x32x16_bf16 v[2:17], v[78:81], v[156:159], v[2:17]
	global_load_dwordx4 v[50:53], v[240:241], off offset:1280
	global_load_dwordx4 v[54:57], v[240:241], off offset:1296
	global_load_dwordx4 v[58:61], v[240:241], off offset:1312
	global_load_dwordx4 v[62:65], v[240:241], off offset:1328
	global_load_dwordx4 v[66:69], v[240:241], off offset:1408
	global_load_dwordx4 v[70:73], v[240:241], off offset:1424
	global_load_dwordx4 v[74:77], v[240:241], off offset:1440
	global_load_dwordx4 v[78:81], v[240:241], off offset:1456
	ds_read_b128 v[108:111], v96 offset:512
	ds_read_b128 v[112:115], v96 offset:528
	ds_read_b128 v[116:119], v96 offset:544
	ds_read_b128 v[120:123], v96 offset:560
	ds_read_b128 v[124:127], v96 offset:640
	ds_read_b128 v[148:151], v96 offset:656
	ds_read_b128 v[152:155], v96 offset:672
	ds_read_b128 v[156:159], v96 offset:688
	s_waitcnt vmcnt(31) lgkmcnt(7)
; #define LAS __attribute__((address_space(3)))
; DI void phase_gates(const Params& P, int l, int bid, int nb, LAS unsigned char* lds) {
;     ...
;         for (int kb = 0; kb < DM; kb += 128) {
;             if (kb + 128 < DM) {
; #pragma unroll
;                 for (int j = 0; j < 8; ++j) an[j] = *(const bf16x8*)(ap + kb + 128 + (j >> 2) * 64 + 8 * (j & 3)); }
; #pragma unroll
;             for (int j = 0; j < 8; ++j) { const bf16x8 bj = *(const LAS bf16x8*)(bp + (kb + (j >> 2) * 64 + 8 * (j & 3)) * 2);
;                 acc = __builtin_amdgcn_mfma_f32_32x32x16_bf16(a[j], bj, acc, 0, 0, 0); }
; #pragma unroll
;             for (int j = 0; j < 8; ++j) a[j] = an[j];
	v_mfma_f32_32x32x16_bf16 v[2:17], v[164:167], v[108:111], v[2:17]
	s_waitcnt vmcnt(30) lgkmcnt(6)
	v_mfma_f32_32x32x16_bf16 v[2:17], v[168:171], v[112:115], v[2:17]
	s_waitcnt vmcnt(29) lgkmcnt(5)
	v_mfma_f32_32x32x16_bf16 v[2:17], v[172:175], v[116:119], v[2:17]
	s_waitcnt vmcnt(28) lgkmcnt(4)
	v_mfma_f32_32x32x16_bf16 v[2:17], v[176:179], v[120:123], v[2:17]
	s_waitcnt vmcnt(27) lgkmcnt(3)
	v_mfma_f32_32x32x16_bf16 v[2:17], v[180:183], v[124:127], v[2:17]
	s_waitcnt vmcnt(26) lgkmcnt(2)
	v_mfma_f32_32x32x16_bf16 v[2:17], v[184:187], v[148:151], v[2:17]
	s_waitcnt vmcnt(25) lgkmcnt(1)
	v_mfma_f32_32x32x16_bf16 v[2:17], v[188:191], v[152:155], v[2:17]
	s_waitcnt vmcnt(24) lgkmcnt(0)
	v_mfma_f32_32x32x16_bf16 v[2:17], v[192:195], v[156:159], v[2:17]
	global_load_dwordx4 v[164:167], v[240:241], off offset:1536
	global_load_dwordx4 v[168:171], v[240:241], off offset:1552
	global_load_dwordx4 v[172:175], v[240:241], off offset:1568
	global_load_dwordx4 v[176:179], v[240:241], off offset:1584
	global_load_dwordx4 v[180:183], v[240:241], off offset:1664
	global_load_dwordx4 v[184:187], v[240:241], off offset:1680
	global_load_dwordx4 v[188:191], v[240:241], off offset:1696
	global_load_dwordx4 v[192:195], v[240:241], off offset:1712
	ds_read_b128 v[108:111], v96 offset:768
	ds_read_b128 v[112:115], v96 offset:784
	ds_read_b128 v[116:119], v96 offset:800
	ds_read_b128 v[120:123], v96 offset:816
	ds_read_b128 v[124:127], v96 offset:896
	ds_read_b128 v[148:151], v96 offset:912
	ds_read_b128 v[152:155], v96 offset:928
	ds_read_b128 v[156:159], v96 offset:944
	s_waitcnt vmcnt(31) lgkmcnt(7)
	v_mfma_f32_32x32x16_bf16 v[2:17], v[208:211], v[108:111], v[2:17]
	s_waitcnt vmcnt(30) lgkmcnt(6)
	v_mfma_f32_32x32x16_bf16 v[2:17], v[212:215], v[112:115], v[2:17]
	s_waitcnt vmcnt(29) lgkmcnt(5)
	v_mfma_f32_32x32x16_bf16 v[2:17], v[216:219], v[116:119], v[2:17]
	s_waitcnt vmcnt(28) lgkmcnt(4)
	v_mfma_f32_32x32x16_bf16 v[2:17], v[220:223], v[120:123], v[2:17]
	s_waitcnt vmcnt(27) lgkmcnt(3)
	v_mfma_f32_32x32x16_bf16 v[2:17], v[224:227], v[124:127], v[2:17]
	s_waitcnt vmcnt(26) lgkmcnt(2)
	v_mfma_f32_32x32x16_bf16 v[2:17], v[228:231], v[148:151], v[2:17]
	s_waitcnt vmcnt(25) lgkmcnt(1)
	v_mfma_f32_32x32x16_bf16 v[2:17], v[232:235], v[152:155], v[2:17]
	s_waitcnt vmcnt(24) lgkmcnt(0)
	v_mfma_f32_32x32x16_bf16 v[2:17], v[236:239], v[156:159], v[2:17]
	global_load_dwordx4 v[208:211], v[240:241], off offset:1792
	global_load_dwordx4 v[212:215], v[240:241], off offset:1808
	global_load_dwordx4 v[216:219], v[240:241], off offset:1824
	global_load_dwordx4 v[220:223], v[240:241], off offset:1840
	global_load_dwordx4 v[224:227], v[240:241], off offset:1920
	global_load_dwordx4 v[228:231], v[240:241], off offset:1936
	global_load_dwordx4 v[232:235], v[240:241], off offset:1952
	global_load_dwordx4 v[236:239], v[240:241], off offset:1968
	ds_read_b128 v[108:111], v96 offset:1024
	ds_read_b128 v[112:115], v96 offset:1040
	ds_read_b128 v[116:119], v96 offset:1056
	ds_read_b128 v[120:123], v96 offset:1072
	ds_read_b128 v[124:127], v96 offset:1152
	ds_read_b128 v[148:151], v96 offset:1168
	ds_read_b128 v[152:155], v96 offset:1184
	ds_read_b128 v[156:159], v96 offset:1200
	s_waitcnt vmcnt(31) lgkmcnt(7)
	v_mfma_f32_32x32x16_bf16 v[2:17], v[18:21], v[108:111], v[2:17]
	s_waitcnt vmcnt(30) lgkmcnt(6)
	v_mfma_f32_32x32x16_bf16 v[2:17], v[22:25], v[112:115], v[2:17]
	s_waitcnt vmcnt(29) lgkmcnt(5)
	v_mfma_f32_32x32x16_bf16 v[2:17], v[26:29], v[116:119], v[2:17]
	s_waitcnt vmcnt(28) lgkmcnt(4)
	v_mfma_f32_32x32x16_bf16 v[2:17], v[30:33], v[120:123], v[2:17]
	s_waitcnt vmcnt(27) lgkmcnt(3)
	v_mfma_f32_32x32x16_bf16 v[2:17], v[34:37], v[124:127], v[2:17]
	s_waitcnt vmcnt(26) lgkmcnt(2)
	v_mfma_f32_32x32x16_bf16 v[2:17], v[38:41], v[148:151], v[2:17]
	s_waitcnt vmcnt(25) lgkmcnt(1)
	v_mfma_f32_32x32x16_bf16 v[2:17], v[42:45], v[152:155], v[2:17]
	s_waitcnt vmcnt(24) lgkmcnt(0)
	v_mfma_f32_32x32x16_bf16 v[2:17], v[46:49], v[156:159], v[2:17]
	global_load_dwordx4 v[18:21], v[240:241], off offset:2048
	global_load_dwordx4 v[22:25], v[240:241], off offset:2064
	global_load_dwordx4 v[26:29], v[240:241], off offset:2080
	global_load_dwordx4 v[30:33], v[240:241], off offset:2096
	global_load_dwordx4 v[34:37], v[240:241], off offset:2176
	global_load_dwordx4 v[38:41], v[240:241], off offset:2192
	global_load_dwordx4 v[42:45], v[240:241], off offset:2208
	global_load_dwordx4 v[46:49], v[240:241], off offset:2224
	ds_read_b128 v[108:111], v96 offset:1280
	ds_read_b128 v[112:115], v96 offset:1296
	ds_read_b128 v[116:119], v96 offset:1312
	ds_read_b128 v[120:123], v96 offset:1328
	ds_read_b128 v[124:127], v96 offset:1408
	ds_read_b128 v[148:151], v96 offset:1424
	ds_read_b128 v[152:155], v96 offset:1440
	ds_read_b128 v[156:159], v96 offset:1456
	s_waitcnt vmcnt(31) lgkmcnt(7)
	v_mfma_f32_32x32x16_bf16 v[2:17], v[50:53], v[108:111], v[2:17]
	s_waitcnt vmcnt(30) lgkmcnt(6)
	v_mfma_f32_32x32x16_bf16 v[2:17], v[54:57], v[112:115], v[2:17]
	s_waitcnt vmcnt(29) lgkmcnt(5)
	v_mfma_f32_32x32x16_bf16 v[2:17], v[58:61], v[116:119], v[2:17]
	s_waitcnt vmcnt(28) lgkmcnt(4)
	v_mfma_f32_32x32x16_bf16 v[2:17], v[62:65], v[120:123], v[2:17]
	s_waitcnt vmcnt(27) lgkmcnt(3)
	v_mfma_f32_32x32x16_bf16 v[2:17], v[66:69], v[124:127], v[2:17]
	s_waitcnt vmcnt(26) lgkmcnt(2)
	v_mfma_f32_32x32x16_bf16 v[2:17], v[70:73], v[148:151], v[2:17]
	s_waitcnt vmcnt(25) lgkmcnt(1)
	v_mfma_f32_32x32x16_bf16 v[2:17], v[74:77], v[152:155], v[2:17]
	s_waitcnt vmcnt(24) lgkmcnt(0)
; #define LAS __attribute__((address_space(3)))
; DI void phase_gates(const Params& P, int l, int bid, int nb, LAS unsigned char* lds) {
;     ...
;         for (int kb = 0; kb < DM; kb += 128) {
;             if (kb + 128 < DM) {
; #pragma unroll
;                 for (int j = 0; j < 8; ++j) an[j] = *(const bf16x8*)(ap + kb + 128 + (j >> 2) * 64 + 8 * (j & 3)); }
; #pragma unroll
;             for (int j = 0; j < 8; ++j) { const bf16x8 bj = *(const LAS bf16x8*)(bp + (kb + (j >> 2) * 64 + 8 * (j & 3)) * 2);
;                 acc = __builtin_amdgcn_mfma_f32_32x32x16_bf16(a[j], bj, acc, 0, 0, 0); }
; #pragma unroll
;             for (int j = 0; j < 8; ++j) a[j] = an[j];
	v_mfma_f32_32x32x16_bf16 v[2:17], v[78:81], v[156:159], v[2:17]
	global_load_dwordx4 v[50:53], v[240:241], off offset:2304
	global_load_dwordx4 v[54:57], v[240:241], off offset:2320
	global_load_dwordx4 v[58:61], v[240:241], off offset:2336
	global_load_dwordx4 v[62:65], v[240:241], off offset:2352
	global_load_dwordx4 v[66:69], v[240:241], off offset:2432
	global_load_dwordx4 v[70:73], v[240:241], off offset:2448
	global_load_dwordx4 v[74:77], v[240:241], off offset:2464
	global_load_dwordx4 v[78:81], v[240:241], off offset:2480
	ds_read_b128 v[108:111], v96 offset:1536
	ds_read_b128 v[112:115], v96 offset:1552
	ds_read_b128 v[116:119], v96 offset:1568
	ds_read_b128 v[120:123], v96 offset:1584
	ds_read_b128 v[124:127], v96 offset:1664
	ds_read_b128 v[148:151], v96 offset:1680
	ds_read_b128 v[152:155], v96 offset:1696
	ds_read_b128 v[156:159], v96 offset:1712
	s_waitcnt vmcnt(31) lgkmcnt(7)
	v_mfma_f32_32x32x16_bf16 v[2:17], v[164:167], v[108:111], v[2:17]
	s_waitcnt vmcnt(30) lgkmcnt(6)
	v_mfma_f32_32x32x16_bf16 v[2:17], v[168:171], v[112:115], v[2:17]
	s_waitcnt vmcnt(29) lgkmcnt(5)
	v_mfma_f32_32x32x16_bf16 v[2:17], v[172:175], v[116:119], v[2:17]
	s_waitcnt vmcnt(28) lgkmcnt(4)
	v_mfma_f32_32x32x16_bf16 v[2:17], v[176:179], v[120:123], v[2:17]
	s_waitcnt vmcnt(27) lgkmcnt(3)
	v_mfma_f32_32x32x16_bf16 v[2:17], v[180:183], v[124:127], v[2:17]
	s_waitcnt vmcnt(26) lgkmcnt(2)
	v_mfma_f32_32x32x16_bf16 v[2:17], v[184:187], v[148:151], v[2:17]
	s_waitcnt vmcnt(25) lgkmcnt(1)
	v_mfma_f32_32x32x16_bf16 v[2:17], v[188:191], v[152:155], v[2:17]
	s_waitcnt vmcnt(24) lgkmcnt(0)
	v_mfma_f32_32x32x16_bf16 v[2:17], v[192:195], v[156:159], v[2:17]
	global_load_dwordx4 v[164:167], v[240:241], off offset:2560
	global_load_dwordx4 v[168:171], v[240:241], off offset:2576
	global_load_dwordx4 v[172:175], v[240:241], off offset:2592
	global_load_dwordx4 v[176:179], v[240:241], off offset:2608
	global_load_dwordx4 v[180:183], v[240:241], off offset:2688
	global_load_dwordx4 v[184:187], v[240:241], off offset:2704
	global_load_dwordx4 v[188:191], v[240:241], off offset:2720
	global_load_dwordx4 v[192:195], v[240:241], off offset:2736
	ds_read_b128 v[108:111], v96 offset:1792
	ds_read_b128 v[112:115], v96 offset:1808
	ds_read_b128 v[116:119], v96 offset:1824
	ds_read_b128 v[120:123], v96 offset:1840
	ds_read_b128 v[124:127], v96 offset:1920
	ds_read_b128 v[148:151], v96 offset:1936
	ds_read_b128 v[152:155], v96 offset:1952
	ds_read_b128 v[156:159], v96 offset:1968
	s_waitcnt vmcnt(31) lgkmcnt(7)
	v_mfma_f32_32x32x16_bf16 v[2:17], v[208:211], v[108:111], v[2:17]
	s_waitcnt vmcnt(30) lgkmcnt(6)
	v_mfma_f32_32x32x16_bf16 v[2:17], v[212:215], v[112:115], v[2:17]
	s_waitcnt vmcnt(29) lgkmcnt(5)
	v_mfma_f32_32x32x16_bf16 v[2:17], v[216:219], v[116:119], v[2:17]
	s_waitcnt vmcnt(28) lgkmcnt(4)
	v_mfma_f32_32x32x16_bf16 v[2:17], v[220:223], v[120:123], v[2:17]
	s_waitcnt vmcnt(27) lgkmcnt(3)
	v_mfma_f32_32x32x16_bf16 v[2:17], v[224:227], v[124:127], v[2:17]
	s_waitcnt vmcnt(26) lgkmcnt(2)
	v_mfma_f32_32x32x16_bf16 v[2:17], v[228:231], v[148:151], v[2:17]
	s_waitcnt vmcnt(25) lgkmcnt(1)
	v_mfma_f32_32x32x16_bf16 v[2:17], v[232:235], v[152:155], v[2:17]
	s_waitcnt vmcnt(24) lgkmcnt(0)
	v_mfma_f32_32x32x16_bf16 v[2:17], v[236:239], v[156:159], v[2:17]
	global_load_dwordx4 v[208:211], v[240:241], off offset:2816
	global_load_dwordx4 v[212:215], v[240:241], off offset:2832
	global_load_dwordx4 v[216:219], v[240:241], off offset:2848
	global_load_dwordx4 v[220:223], v[240:241], off offset:2864
	global_load_dwordx4 v[224:227], v[240:241], off offset:2944
	global_load_dwordx4 v[228:231], v[240:241], off offset:2960
	global_load_dwordx4 v[232:235], v[240:241], off offset:2976
	global_load_dwordx4 v[236:239], v[240:241], off offset:2992
	ds_read_b128 v[108:111], v96 offset:2048
	ds_read_b128 v[112:115], v96 offset:2064
	ds_read_b128 v[116:119], v96 offset:2080
	ds_read_b128 v[120:123], v96 offset:2096
	ds_read_b128 v[124:127], v96 offset:2176
	ds_read_b128 v[148:151], v96 offset:2192
	ds_read_b128 v[152:155], v96 offset:2208
	ds_read_b128 v[156:159], v96 offset:2224
	s_waitcnt vmcnt(31) lgkmcnt(7)
	v_mfma_f32_32x32x16_bf16 v[2:17], v[18:21], v[108:111], v[2:17]
	s_waitcnt vmcnt(30) lgkmcnt(6)
	v_mfma_f32_32x32x16_bf16 v[2:17], v[22:25], v[112:115], v[2:17]
	s_waitcnt vmcnt(29) lgkmcnt(5)
	v_mfma_f32_32x32x16_bf16 v[2:17], v[26:29], v[116:119], v[2:17]
	s_waitcnt vmcnt(28) lgkmcnt(4)
	v_mfma_f32_32x32x16_bf16 v[2:17], v[30:33], v[120:123], v[2:17]
	s_waitcnt vmcnt(27) lgkmcnt(3)
	v_mfma_f32_32x32x16_bf16 v[2:17], v[34:37], v[124:127], v[2:17]
	s_waitcnt vmcnt(26) lgkmcnt(2)
	v_mfma_f32_32x32x16_bf16 v[2:17], v[38:41], v[148:151], v[2:17]
	s_waitcnt vmcnt(25) lgkmcnt(1)
	v_mfma_f32_32x32x16_bf16 v[2:17], v[42:45], v[152:155], v[2:17]
	s_waitcnt vmcnt(24) lgkmcnt(0)
	v_mfma_f32_32x32x16_bf16 v[2:17], v[46:49], v[156:159], v[2:17]
	global_load_dwordx4 v[18:21], v[240:241], off offset:3072
	global_load_dwordx4 v[22:25], v[240:241], off offset:3088
	global_load_dwordx4 v[26:29], v[240:241], off offset:3104
	global_load_dwordx4 v[30:33], v[240:241], off offset:3120
	global_load_dwordx4 v[34:37], v[240:241], off offset:3200
	global_load_dwordx4 v[38:41], v[240:241], off offset:3216
	global_load_dwordx4 v[42:45], v[240:241], off offset:3232
	global_load_dwordx4 v[46:49], v[240:241], off offset:3248
	ds_read_b128 v[108:111], v96 offset:2304
	ds_read_b128 v[112:115], v96 offset:2320
	ds_read_b128 v[116:119], v96 offset:2336
	ds_read_b128 v[120:123], v96 offset:2352
	ds_read_b128 v[124:127], v96 offset:2432
	ds_read_b128 v[148:151], v96 offset:2448
	ds_read_b128 v[152:155], v96 offset:2464
	ds_read_b128 v[156:159], v96 offset:2480
	s_waitcnt vmcnt(31) lgkmcnt(7)
; #define LAS __attribute__((address_space(3)))
; DI void phase_gates(const Params& P, int l, int bid, int nb, LAS unsigned char* lds) {
;     ...
;         for (int kb = 0; kb < DM; kb += 128) {
;             if (kb + 128 < DM) {
; #pragma unroll
;                 for (int j = 0; j < 8; ++j) an[j] = *(const bf16x8*)(ap + kb + 128 + (j >> 2) * 64 + 8 * (j & 3)); }
; #pragma unroll
;             for (int j = 0; j < 8; ++j) { const bf16x8 bj = *(const LAS bf16x8*)(bp + (kb + (j >> 2) * 64 + 8 * (j & 3)) * 2);
;                 acc = __builtin_amdgcn_mfma_f32_32x32x16_bf16(a[j], bj, acc, 0, 0, 0); }
; #pragma unroll
;             for (int j = 0; j < 8; ++j) a[j] = an[j];
	v_mfma_f32_32x32x16_bf16 v[2:17], v[50:53], v[108:111], v[2:17]
	s_waitcnt vmcnt(30) lgkmcnt(6)
	v_mfma_f32_32x32x16_bf16 v[2:17], v[54:57], v[112:115], v[2:17]
	s_waitcnt vmcnt(29) lgkmcnt(5)
	v_mfma_f32_32x32x16_bf16 v[2:17], v[58:61], v[116:119], v[2:17]
	s_waitcnt vmcnt(28) lgkmcnt(4)
	v_mfma_f32_32x32x16_bf16 v[2:17], v[62:65], v[120:123], v[2:17]
	s_waitcnt vmcnt(27) lgkmcnt(3)
	v_mfma_f32_32x32x16_bf16 v[2:17], v[66:69], v[124:127], v[2:17]
	s_waitcnt vmcnt(26) lgkmcnt(2)
	v_mfma_f32_32x32x16_bf16 v[2:17], v[70:73], v[148:151], v[2:17]
	s_waitcnt vmcnt(25) lgkmcnt(1)
	v_mfma_f32_32x32x16_bf16 v[2:17], v[74:77], v[152:155], v[2:17]
	s_waitcnt vmcnt(24) lgkmcnt(0)
	v_mfma_f32_32x32x16_bf16 v[2:17], v[78:81], v[156:159], v[2:17]
	global_load_dwordx4 v[50:53], v[240:241], off offset:3328
	global_load_dwordx4 v[54:57], v[240:241], off offset:3344
	global_load_dwordx4 v[58:61], v[240:241], off offset:3360
	global_load_dwordx4 v[62:65], v[240:241], off offset:3376
	global_load_dwordx4 v[66:69], v[240:241], off offset:3456
	global_load_dwordx4 v[70:73], v[240:241], off offset:3472
	global_load_dwordx4 v[74:77], v[240:241], off offset:3488
	global_load_dwordx4 v[78:81], v[240:241], off offset:3504
	ds_read_b128 v[108:111], v96 offset:2560
	ds_read_b128 v[112:115], v96 offset:2576
	ds_read_b128 v[116:119], v96 offset:2592
	ds_read_b128 v[120:123], v96 offset:2608
	ds_read_b128 v[124:127], v96 offset:2688
	ds_read_b128 v[148:151], v96 offset:2704
	ds_read_b128 v[152:155], v96 offset:2720
	ds_read_b128 v[156:159], v96 offset:2736
	s_waitcnt vmcnt(31) lgkmcnt(7)
	v_mfma_f32_32x32x16_bf16 v[2:17], v[164:167], v[108:111], v[2:17]
	s_waitcnt vmcnt(30) lgkmcnt(6)
	v_mfma_f32_32x32x16_bf16 v[2:17], v[168:171], v[112:115], v[2:17]
	s_waitcnt vmcnt(29) lgkmcnt(5)
	v_mfma_f32_32x32x16_bf16 v[2:17], v[172:175], v[116:119], v[2:17]
	s_waitcnt vmcnt(28) lgkmcnt(4)
	v_mfma_f32_32x32x16_bf16 v[2:17], v[176:179], v[120:123], v[2:17]
	s_waitcnt vmcnt(27) lgkmcnt(3)
	v_mfma_f32_32x32x16_bf16 v[2:17], v[180:183], v[124:127], v[2:17]
	s_waitcnt vmcnt(26) lgkmcnt(2)
	v_mfma_f32_32x32x16_bf16 v[2:17], v[184:187], v[148:151], v[2:17]
	s_waitcnt vmcnt(25) lgkmcnt(1)
	v_mfma_f32_32x32x16_bf16 v[2:17], v[188:191], v[152:155], v[2:17]
	s_waitcnt vmcnt(24) lgkmcnt(0)
	v_mfma_f32_32x32x16_bf16 v[2:17], v[192:195], v[156:159], v[2:17]
	global_load_dwordx4 v[164:167], v[240:241], off offset:3584
	global_load_dwordx4 v[168:171], v[240:241], off offset:3600
	global_load_dwordx4 v[172:175], v[240:241], off offset:3616
	global_load_dwordx4 v[176:179], v[240:241], off offset:3632
	global_load_dwordx4 v[180:183], v[240:241], off offset:3712
	global_load_dwordx4 v[184:187], v[240:241], off offset:3728
	global_load_dwordx4 v[188:191], v[240:241], off offset:3744
	global_load_dwordx4 v[192:195], v[240:241], off offset:3760
	ds_read_b128 v[108:111], v96 offset:2816
	ds_read_b128 v[112:115], v96 offset:2832
	ds_read_b128 v[116:119], v96 offset:2848
	ds_read_b128 v[120:123], v96 offset:2864
	ds_read_b128 v[124:127], v96 offset:2944
	ds_read_b128 v[148:151], v96 offset:2960
	ds_read_b128 v[152:155], v96 offset:2976
	ds_read_b128 v[156:159], v96 offset:2992
	s_waitcnt vmcnt(31) lgkmcnt(7)
	v_mfma_f32_32x32x16_bf16 v[2:17], v[208:211], v[108:111], v[2:17]
	s_waitcnt vmcnt(30) lgkmcnt(6)
	v_mfma_f32_32x32x16_bf16 v[2:17], v[212:215], v[112:115], v[2:17]
	s_waitcnt vmcnt(29) lgkmcnt(5)
	v_mfma_f32_32x32x16_bf16 v[2:17], v[216:219], v[116:119], v[2:17]
	s_waitcnt vmcnt(28) lgkmcnt(4)
	v_mfma_f32_32x32x16_bf16 v[2:17], v[220:223], v[120:123], v[2:17]
	s_waitcnt vmcnt(27) lgkmcnt(3)
	v_mfma_f32_32x32x16_bf16 v[2:17], v[224:227], v[124:127], v[2:17]
	s_waitcnt vmcnt(26) lgkmcnt(2)
	v_mfma_f32_32x32x16_bf16 v[2:17], v[228:231], v[148:151], v[2:17]
	s_waitcnt vmcnt(25) lgkmcnt(1)
	v_mfma_f32_32x32x16_bf16 v[2:17], v[232:235], v[152:155], v[2:17]
	s_waitcnt vmcnt(24) lgkmcnt(0)
	v_mfma_f32_32x32x16_bf16 v[2:17], v[236:239], v[156:159], v[2:17]
	global_load_dwordx4 v[208:211], v[240:241], off offset:3840
	global_load_dwordx4 v[212:215], v[240:241], off offset:3856
	global_load_dwordx4 v[216:219], v[240:241], off offset:3872
	global_load_dwordx4 v[220:223], v[240:241], off offset:3888
	global_load_dwordx4 v[224:227], v[240:241], off offset:3968
	global_load_dwordx4 v[228:231], v[240:241], off offset:3984
	global_load_dwordx4 v[232:235], v[240:241], off offset:4000
	global_load_dwordx4 v[236:239], v[240:241], off offset:4016
	ds_read_b128 v[108:111], v96 offset:3072
	ds_read_b128 v[112:115], v96 offset:3088
	ds_read_b128 v[116:119], v96 offset:3104
	ds_read_b128 v[120:123], v96 offset:3120
	ds_read_b128 v[124:127], v96 offset:3200
	ds_read_b128 v[148:151], v96 offset:3216
	ds_read_b128 v[152:155], v96 offset:3232
	ds_read_b128 v[156:159], v96 offset:3248
	s_waitcnt vmcnt(31) lgkmcnt(7)
; #define LAS __attribute__((address_space(3)))
; DI void phase_gates(const Params& P, int l, int bid, int nb, LAS unsigned char* lds) {
;     ...
;         for (int kb = 0; kb < DM; kb += 128) {
;             if (kb + 128 < DM) {
; #pragma unroll
;                 for (int j = 0; j < 8; ++j) an[j] = *(const bf16x8*)(ap + kb + 128 + (j >> 2) * 64 + 8 * (j & 3)); }
; #pragma unroll
;             for (int j = 0; j < 8; ++j) { const bf16x8 bj = *(const LAS bf16x8*)(bp + (kb + (j >> 2) * 64 + 8 * (j & 3)) * 2);
;                 acc = __builtin_amdgcn_mfma_f32_32x32x16_bf16(a[j], bj, acc, 0, 0, 0); }
; #pragma unroll
;             for (int j = 0; j < 8; ++j) a[j] = an[j];
;         }
	v_mfma_f32_32x32x16_bf16 v[2:17], v[18:21], v[108:111], v[2:17]
	s_waitcnt vmcnt(30) lgkmcnt(6)
	v_mfma_f32_32x32x16_bf16 v[2:17], v[22:25], v[112:115], v[2:17]
	s_waitcnt vmcnt(29) lgkmcnt(5)
	v_mfma_f32_32x32x16_bf16 v[2:17], v[26:29], v[116:119], v[2:17]
	s_waitcnt vmcnt(28) lgkmcnt(4)
	v_mfma_f32_32x32x16_bf16 v[2:17], v[30:33], v[120:123], v[2:17]
	s_waitcnt vmcnt(27) lgkmcnt(3)
	v_mfma_f32_32x32x16_bf16 v[2:17], v[34:37], v[124:127], v[2:17]
	s_waitcnt vmcnt(26) lgkmcnt(2)
	v_mfma_f32_32x32x16_bf16 v[2:17], v[38:41], v[148:151], v[2:17]
	s_waitcnt vmcnt(25) lgkmcnt(1)
	v_mfma_f32_32x32x16_bf16 v[2:17], v[42:45], v[152:155], v[2:17]
	s_waitcnt vmcnt(24) lgkmcnt(0)
	v_mfma_f32_32x32x16_bf16 v[2:17], v[46:49], v[156:159], v[2:17]
	ds_read_b128 v[108:111], v96 offset:3328
	ds_read_b128 v[112:115], v96 offset:3344
	ds_read_b128 v[116:119], v96 offset:3360
	ds_read_b128 v[120:123], v96 offset:3376
	ds_read_b128 v[124:127], v96 offset:3456
	ds_read_b128 v[148:151], v96 offset:3472
	ds_read_b128 v[152:155], v96 offset:3488
	ds_read_b128 v[156:159], v96 offset:3504
	s_waitcnt vmcnt(23) lgkmcnt(7)
	v_mfma_f32_32x32x16_bf16 v[2:17], v[50:53], v[108:111], v[2:17]
	s_waitcnt vmcnt(22) lgkmcnt(6)
	v_mfma_f32_32x32x16_bf16 v[2:17], v[54:57], v[112:115], v[2:17]
	s_waitcnt vmcnt(21) lgkmcnt(5)
	v_mfma_f32_32x32x16_bf16 v[2:17], v[58:61], v[116:119], v[2:17]
	s_waitcnt vmcnt(20) lgkmcnt(4)
	v_mfma_f32_32x32x16_bf16 v[2:17], v[62:65], v[120:123], v[2:17]
	s_waitcnt vmcnt(19) lgkmcnt(3)
	v_mfma_f32_32x32x16_bf16 v[2:17], v[66:69], v[124:127], v[2:17]
	s_waitcnt vmcnt(18) lgkmcnt(2)
	v_mfma_f32_32x32x16_bf16 v[2:17], v[70:73], v[148:151], v[2:17]
	s_waitcnt vmcnt(17) lgkmcnt(1)
	v_mfma_f32_32x32x16_bf16 v[2:17], v[74:77], v[152:155], v[2:17]
	s_waitcnt vmcnt(16) lgkmcnt(0)
	v_mfma_f32_32x32x16_bf16 v[2:17], v[78:81], v[156:159], v[2:17]
	ds_read_b128 v[108:111], v96 offset:3584
	ds_read_b128 v[112:115], v96 offset:3600
	ds_read_b128 v[116:119], v96 offset:3616
	ds_read_b128 v[120:123], v96 offset:3632
	ds_read_b128 v[124:127], v96 offset:3712
	ds_read_b128 v[148:151], v96 offset:3728
	ds_read_b128 v[152:155], v96 offset:3744
	ds_read_b128 v[156:159], v96 offset:3760
	s_waitcnt vmcnt(15) lgkmcnt(7)
	v_mfma_f32_32x32x16_bf16 v[2:17], v[164:167], v[108:111], v[2:17]
	s_waitcnt vmcnt(14) lgkmcnt(6)
	v_mfma_f32_32x32x16_bf16 v[2:17], v[168:171], v[112:115], v[2:17]
	s_waitcnt vmcnt(13) lgkmcnt(5)
	v_mfma_f32_32x32x16_bf16 v[2:17], v[172:175], v[116:119], v[2:17]
	s_waitcnt vmcnt(12) lgkmcnt(4)
	v_mfma_f32_32x32x16_bf16 v[2:17], v[176:179], v[120:123], v[2:17]
	s_waitcnt vmcnt(11) lgkmcnt(3)
	v_mfma_f32_32x32x16_bf16 v[2:17], v[180:183], v[124:127], v[2:17]
	s_waitcnt vmcnt(10) lgkmcnt(2)
	v_mfma_f32_32x32x16_bf16 v[2:17], v[184:187], v[148:151], v[2:17]
	s_waitcnt vmcnt(9) lgkmcnt(1)
	v_mfma_f32_32x32x16_bf16 v[2:17], v[188:191], v[152:155], v[2:17]
	s_waitcnt vmcnt(8) lgkmcnt(0)
	v_mfma_f32_32x32x16_bf16 v[2:17], v[192:195], v[156:159], v[2:17]
	ds_read_b128 v[108:111], v96 offset:3840
	ds_read_b128 v[112:115], v96 offset:3856
	ds_read_b128 v[116:119], v96 offset:3872
	ds_read_b128 v[120:123], v96 offset:3888
	ds_read_b128 v[124:127], v96 offset:3968
	ds_read_b128 v[148:151], v96 offset:3984
	ds_read_b128 v[152:155], v96 offset:4000
	ds_read_b128 v[156:159], v96 offset:4016
	s_waitcnt vmcnt(7) lgkmcnt(7)
	v_mfma_f32_32x32x16_bf16 v[2:17], v[208:211], v[108:111], v[2:17]
	s_waitcnt vmcnt(6) lgkmcnt(6)
	v_mfma_f32_32x32x16_bf16 v[2:17], v[212:215], v[112:115], v[2:17]
	s_waitcnt vmcnt(5) lgkmcnt(5)
	v_mfma_f32_32x32x16_bf16 v[2:17], v[216:219], v[116:119], v[2:17]
	s_waitcnt vmcnt(4) lgkmcnt(4)
	v_mfma_f32_32x32x16_bf16 v[2:17], v[220:223], v[120:123], v[2:17]
	s_waitcnt vmcnt(3) lgkmcnt(3)
	v_mfma_f32_32x32x16_bf16 v[2:17], v[224:227], v[124:127], v[2:17]
	s_waitcnt vmcnt(2) lgkmcnt(2)
	v_mfma_f32_32x32x16_bf16 v[2:17], v[228:231], v[148:151], v[2:17]
	s_waitcnt vmcnt(1) lgkmcnt(1)
	v_mfma_f32_32x32x16_bf16 v[2:17], v[232:235], v[152:155], v[2:17]
	s_waitcnt vmcnt(0) lgkmcnt(0)
	v_mfma_f32_32x32x16_bf16 v[2:17], v[236:239], v[156:159], v[2:17]
	s_branch .LBB0_189
